# poll loops: s_sleep 10 instead of s_sleep 1 between polls of the release counter (fewer polls from waiting workgroups while stragglers still compute)
# speedup vs baseline: 1.0055x; 1.0024x over previous
; DI unsigned xb_ld(unsigned* p)              { return __hip_atomic_load(p, __ATOMIC_RELAXED, __HIP_MEMORY_SCOPE_AGENT); }
; #define XB_SPIN(cond, bar) do { unsigned _sp = 0; while (cond) { __builtin_amdgcn_s_sleep(1); \
;     if ((++_sp & 255u) == 0u) { if (xb_ld(&(bar)[XB_TMO])) break; if (_sp > XB_SPIN_CAP) { atomicAdd(&(bar)[XB_TMO], 1u); break; } } } } while (0)
; DI void xcd_barrier(unsigned* bar, volatile __attribute__((address_space(3))) unsigned* st) {
;     ...
;             XB_SPIN(xb_ld(&bar[XB_XGEN(x)]) == gen, bar);
.Lnlf_p1:
	global_load_dword v3, v2, s[70:71] offset:1280 sc1
	s_waitcnt vmcnt(0)
	v_cmp_lt_u32_e32 vcc, v3, v4
	s_cbranch_vccz .Lnlf_d1
	s_sleep 10
	s_branch .Lnlf_p1
